# hoist the 7 per-row-group rowsq loads of the FFN-up SwiGLU epilogue to its top and drop the per-group vmcnt(0) waits
# speedup vs baseline: 1.0073x; 1.0073x over previous
; __device__ __forceinline__ float sigm(float v) { return __builtin_amdgcn_rcpf(1.f + __builtin_amdgcn_exp2f(-1.4426950408889634f * v)); }
; __device__ __forceinline__ unsigned pkbf(float lo, float hi) { return pg8::cvt_pk_bf16(lo, hi); }
;     __device__ __forceinline__ void operator()(const f32x4 (&acc)[2][2][4][2], const Unit& u, int wr, int wc, int fr, int fq) const {
;         const int pn = u.pn, pm = u.pm;
;         const int v = pm >= 64 ? 2 : (pm >> 5);
;         const int cb = pn * 256 + wc * 32 + 8 * fq;
;         f32x4 bv[2][2];
; #pragma unroll
;         for (int bj = 0; bj < 2; ++bj)
; #pragma unroll
;             for (int n = 0; n < 2; ++n) bv[bj][n] = *(const f32x4*)(bias + v * FFI + cb + 128 * bj + 4 * n);
; #pragma unroll
;         for (int ai = 0; ai < 2; ++ai)
; #pragma unroll
;             for (int m = 0; m < 4; ++m) {
;                 const int row = pm * 256 + ai * 128 + wr * 64 + m * 16 + fr;
;                 const float rinv = rsqrtf(rowsq[row] * (1.f / DM) + EPSN);
;                 f32x4 o[2];
; #pragma unroll
;                 for (int n = 0; n < 2; ++n) {
;                     const f32x4 g = acc[ai][0][m][n] * rinv + bv[0][n], up = acc[ai][1][m][n] * rinv + bv[1][n];
; #pragma unroll
;                     for (int j = 0; j < 4; ++j) o[n][j] = g[j] * sigm(g[j]) * up[j];
;                 }
;                 u32x4 w; w.x = pkbf(o[0][0], o[0][1]); w.y = pkbf(o[0][2], o[0][3]); w.z = pkbf(o[1][0], o[1][1]); w.w = pkbf(o[1][2], o[1][3]);
;                 *(u32x4*)(act + (size_t)row * FFH + pn * 128 + wc * 32 + 8 * fq) = w;
;             }
;     }
.LBB0_1092:
	v_lshl_add_u32 v148, s26, 8, v152
	v_ashrrev_i32_e32 v149, 31, v148
	v_lshl_add_u64 v[150:151], v[148:149], 2, s[10:11]
	s_min_i32 s1, s26, 64
	flat_load_dword v149, v[150:151]
	flat_load_dword v182, v[150:151] offset:64
	flat_load_dword v183, v[150:151] offset:128
	flat_load_dword v184, v[150:151] offset:192
	flat_load_dword v185, v[150:151] offset:512
	flat_load_dword v186, v[150:151] offset:576
	flat_load_dword v187, v[150:151] offset:640
	flat_load_dword v188, v[150:151] offset:704
	s_lshr_b32 s1, s1, 5
	s_mul_i32 s28, s1, 0x1600
	s_ashr_i32 s29, s28, 31
	s_lshl_b64 s[28:29], s[28:29], 2
	v_lshl_or_b32 v80, s0, 8, v154
	s_add_u32 s26, s38, s28
	s_addc_u32 s27, s39, s29
	v_ashrrev_i32_e32 v81, 31, v80
	v_lshl_add_u64 v[80:81], v[80:81], 2, s[26:27]
	flat_load_dwordx4 v[156:159], v[80:81] offset:512
	flat_load_dwordx4 v[84:87], v[80:81]
	flat_load_dwordx4 v[160:163], v[80:81] offset:528
	s_nop 0
	flat_load_dwordx4 v[80:83], v[80:81] offset:16
	v_mov_b32_e32 v168, v120
	v_mov_b32_e32 v169, v124
	v_mov_b32_e32 v124, v121
	v_mov_b32_e32 v164, v132
	v_mov_b32_e32 v165, v128
	v_mov_b32_e32 v128, v133
	v_mov_b32_e32 v166, v134
	v_mov_b32_e32 v167, v130
	v_mov_b32_e32 v130, v135
	v_mov_b32_e32 v170, v122
	v_mov_b32_e32 v171, v126
	v_mov_b32_e32 v126, v123
	s_lshl_b32 s0, s0, 7
	s_ashr_i32 s1, s0, 31
	s_waitcnt vmcnt(0) lgkmcnt(0)
	v_fmamk_f32 v120, v149, 0x3a800000, v224
	v_mul_f32_e32 v121, 0x4b800000, v120
	v_cmp_gt_f32_e32 vcc, s33, v120
	v_mov_b32_e32 v122, v158
	s_nop 0
	v_cndmask_b32_e32 v120, v120, v121, vcc
	v_rsq_f32_e32 v149, v120
	v_mov_b32_e32 v120, v156
	v_mov_b32_e32 v121, v84
	v_mov_b32_e32 v84, v157
	v_mul_f32_e32 v156, 0x45800000, v149
	v_mov_b32_e32 v123, v86
	v_mov_b32_e32 v133, v80
	v_mov_b32_e32 v80, v161
	v_mov_b32_e32 v134, v162
	v_mov_b32_e32 v135, v82
	v_cndmask_b32_e32 v156, v149, v156, vcc
	v_mov_b32_e32 v86, v159
	v_mov_b32_e32 v132, v160
	v_mov_b32_e32 v82, v163
	v_pk_fma_f32 v[158:159], v[164:165], v[156:157], v[120:121] op_sel_hi:[1,0,1]
	v_pk_fma_f32 v[128:129], v[128:129], v[156:157], v[84:85] op_sel_hi:[1,0,1]
	v_pk_fma_f32 v[160:161], v[166:167], v[156:157], v[122:123] op_sel_hi:[1,0,1]
	v_pk_fma_f32 v[124:125], v[124:125], v[156:157], v[80:81] op_sel_hi:[1,0,1]
	v_pk_fma_f32 v[164:165], v[170:171], v[156:157], v[134:135] op_sel_hi:[1,0,1]
	v_pk_fma_f32 v[130:131], v[130:131], v[156:157], v[86:87] op_sel_hi:[1,0,1]
	v_pk_fma_f32 v[162:163], v[168:169], v[156:157], v[132:133] op_sel_hi:[1,0,1]
	v_pk_fma_f32 v[126:127], v[126:127], v[156:157], v[82:83] op_sel_hi:[1,0,1]
	v_mul_f32_e32 v149, 0xbfb8aa3b, v159
	v_mul_f32_e32 v156, 0xbfb8aa3b, v129
	v_mul_f32_e32 v157, 0xbfb8aa3b, v161
	v_mul_f32_e32 v168, 0xbfb8aa3b, v125
	v_mul_f32_e32 v169, 0xbfb8aa3b, v165
	v_mul_f32_e32 v166, 0xbfb8aa3b, v131
	v_mul_f32_e32 v167, 0xbfb8aa3b, v163
	v_mul_f32_e32 v170, 0xbfb8aa3b, v127
	v_exp_f32_e32 v149, v149
	v_exp_f32_e32 v156, v156
	v_exp_f32_e32 v157, v157
	v_exp_f32_e32 v168, v168
	v_exp_f32_e32 v169, v169
	v_exp_f32_e32 v166, v166
	v_exp_f32_e32 v167, v167
	v_exp_f32_e32 v170, v170
	v_add_f32_e32 v149, 1.0, v149
	v_add_f32_e32 v156, 1.0, v156
	v_add_f32_e32 v157, 1.0, v157
	v_add_f32_e32 v168, 1.0, v168
	v_add_f32_e32 v169, 1.0, v169
	v_add_f32_e32 v166, 1.0, v166
	v_add_f32_e32 v167, 1.0, v167
	v_add_f32_e32 v170, 1.0, v170
	v_rcp_f32_e32 v149, v149
	v_rcp_f32_e32 v156, v156
	v_rcp_f32_e32 v157, v157
	v_rcp_f32_e32 v168, v168
	v_rcp_f32_e32 v169, v169
	v_rcp_f32_e32 v166, v166
	v_rcp_f32_e32 v167, v167
	v_rcp_f32_e32 v170, v170
	v_mul_f32_e32 v149, v159, v149
	v_mul_f32_e32 v129, v129, v156
	v_mul_f32_e32 v156, v161, v157
	v_mul_f32_e32 v125, v125, v168
	v_mul_f32_e32 v159, v165, v169
	v_mul_f32_e32 v131, v131, v166
	v_mul_f32_e32 v157, v163, v167
	v_mul_f32_e32 v128, v128, v129
	v_mul_f32_e32 v129, v160, v156
	v_mul_f32_e32 v124, v124, v125
	v_mul_f32_e32 v125, v164, v159
	v_mul_f32_e32 v127, v127, v170
	v_mul_f32_e32 v149, v158, v149
	v_mul_f32_e32 v130, v130, v131
	v_mul_f32_e32 v131, v162, v157
	v_mul_f32_e32 v156, v126, v127
	v_cvt_pk_bf16_f32 v126, v149, v128
	v_cvt_pk_bf16_f32 v127, v129, v130
	v_cvt_pk_bf16_f32 v128, v131, v124
	v_cvt_pk_bf16_f32 v129, v125, v156
	v_mov_b64_e32 v[124:125], s[12:13]
	v_mad_i64_i32 v[130:131], s[26:27], v148, s3, v[124:125]
	s_lshl_b64 s[26:27], s[0:1], 1
	s_nop 0
	v_lshl_add_u64 v[130:131], v[130:131], 0, s[26:27]
	v_lshl_add_u64 v[130:131], v[130:131], 0, s[76:77]
	v_lshl_add_u64 v[130:131], v[130:131], 0, v[176:177]
	flat_store_dwordx4 v[130:131], v[126:129]
	s_nop 0
	s_nop 0
	v_mov_b32_e32 v127, v112
	v_mov_b32_e32 v112, v117
	v_mov_b32_e32 v117, v114
	v_mov_b32_e32 v114, v119
	v_mov_b32_e32 v119, v104
	v_mov_b32_e32 v104, v109
	v_mov_b32_e32 v109, v106
	v_mov_b32_e32 v106, v111
	v_mov_b32_e32 v126, v116
	v_mov_b32_e32 v116, v118
	v_mov_b32_e32 v118, v108
	v_mov_b32_e32 v108, v110
	v_or_b32_e32 v110, 16, v148
	v_mad_i64_i32 v[110:111], s[0:1], v110, s3, v[124:125]
	v_lshl_add_u64 v[110:111], v[110:111], 0, s[26:27]
	v_lshl_add_u64 v[110:111], v[110:111], 0, s[76:77]
	v_lshl_add_u64 v[110:111], v[110:111], 0, v[176:177]
	v_fmamk_f32 v128, v182, 0x3a800000, v224
	v_mul_f32_e32 v129, 0x4b800000, v128
	v_cmp_gt_f32_e32 vcc, s33, v128
	s_nop 1
	v_cndmask_b32_e32 v128, v128, v129, vcc
	v_rsq_f32_e32 v128, v128
	s_nop 0
	v_mul_f32_e32 v129, 0x45800000, v128
	v_cndmask_b32_e32 v128, v128, v129, vcc
	v_pk_fma_f32 v[106:107], v[106:107], v[128:129], v[82:83] op_sel_hi:[1,0,1]
	v_pk_fma_f32 v[126:127], v[126:127], v[128:129], v[120:121] op_sel_hi:[1,0,1]
	v_pk_fma_f32 v[112:113], v[112:113], v[128:129], v[84:85] op_sel_hi:[1,0,1]
	v_pk_fma_f32 v[116:117], v[116:117], v[128:129], v[122:123] op_sel_hi:[1,0,1]
; __device__ __forceinline__ float sigm(float v) { return __builtin_amdgcn_rcpf(1.f + __builtin_amdgcn_exp2f(-1.4426950408889634f * v)); }
; __device__ __forceinline__ unsigned pkbf(float lo, float hi) { return pg8::cvt_pk_bf16(lo, hi); }
;     __device__ __forceinline__ void operator()(const f32x4 (&acc)[2][2][4][2], const Unit& u, int wr, int wc, int fr, int fq) const {
;         const int pn = u.pn, pm = u.pm;
;         const int v = pm >= 64 ? 2 : (pm >> 5);
;         const int cb = pn * 256 + wc * 32 + 8 * fq;
;         f32x4 bv[2][2];
; #pragma unroll
;         for (int bj = 0; bj < 2; ++bj)
; #pragma unroll
;             for (int n = 0; n < 2; ++n) bv[bj][n] = *(const f32x4*)(bias + v * FFI + cb + 128 * bj + 4 * n);
; #pragma unroll
;         for (int ai = 0; ai < 2; ++ai)
; #pragma unroll
;             for (int m = 0; m < 4; ++m) {
;                 const int row = pm * 256 + ai * 128 + wr * 64 + m * 16 + fr;
;                 const float rinv = rsqrtf(rowsq[row] * (1.f / DM) + EPSN);
;                 f32x4 o[2];
; #pragma unroll
;                 for (int n = 0; n < 2; ++n) {
;                     const f32x4 g = acc[ai][0][m][n] * rinv + bv[0][n], up = acc[ai][1][m][n] * rinv + bv[1][n];
; #pragma unroll
;                     for (int j = 0; j < 4; ++j) o[n][j] = g[j] * sigm(g[j]) * up[j];
;                 }
;                 u32x4 w; w.x = pkbf(o[0][0], o[0][1]); w.y = pkbf(o[0][2], o[0][3]); w.z = pkbf(o[1][0], o[1][1]); w.w = pkbf(o[1][2], o[1][3]);
;                 *(u32x4*)(act + (size_t)row * FFH + pn * 128 + wc * 32 + 8 * fq) = w;
;             }
;     }
	v_pk_fma_f32 v[114:115], v[114:115], v[128:129], v[86:87] op_sel_hi:[1,0,1]
	v_pk_fma_f32 v[118:119], v[118:119], v[128:129], v[132:133] op_sel_hi:[1,0,1]
	v_pk_fma_f32 v[104:105], v[104:105], v[128:129], v[80:81] op_sel_hi:[1,0,1]
	v_pk_fma_f32 v[108:109], v[108:109], v[128:129], v[134:135] op_sel_hi:[1,0,1]
	v_mul_f32_e32 v158, 0xbfb8aa3b, v107
	v_mul_f32_e32 v128, 0xbfb8aa3b, v127
	v_mul_f32_e32 v129, 0xbfb8aa3b, v113
	v_mul_f32_e32 v130, 0xbfb8aa3b, v117
	v_mul_f32_e32 v131, 0xbfb8aa3b, v115
	v_mul_f32_e32 v149, 0xbfb8aa3b, v119
	v_mul_f32_e32 v156, 0xbfb8aa3b, v105
	v_mul_f32_e32 v157, 0xbfb8aa3b, v109
	v_exp_f32_e32 v158, v158
	v_exp_f32_e32 v128, v128
	v_exp_f32_e32 v129, v129
	v_exp_f32_e32 v130, v130
	v_exp_f32_e32 v131, v131
	v_exp_f32_e32 v149, v149
	v_exp_f32_e32 v156, v156
	v_exp_f32_e32 v157, v157
	v_add_f32_e32 v158, 1.0, v158
	v_add_f32_e32 v128, 1.0, v128
	v_add_f32_e32 v129, 1.0, v129
	v_add_f32_e32 v130, 1.0, v130
	v_add_f32_e32 v131, 1.0, v131
	v_add_f32_e32 v149, 1.0, v149
	v_add_f32_e32 v156, 1.0, v156
	v_add_f32_e32 v157, 1.0, v157
	v_rcp_f32_e32 v158, v158
	v_rcp_f32_e32 v128, v128
	v_rcp_f32_e32 v129, v129
	v_rcp_f32_e32 v130, v130
	v_rcp_f32_e32 v131, v131
	v_rcp_f32_e32 v149, v149
	v_rcp_f32_e32 v156, v156
	v_rcp_f32_e32 v157, v157
	v_mul_f32_e32 v107, v107, v158
	v_mul_f32_e32 v127, v127, v128
	v_mul_f32_e32 v113, v113, v129
	v_mul_f32_e32 v117, v117, v130
	v_mul_f32_e32 v115, v115, v131
	v_mul_f32_e32 v119, v119, v149
	v_mul_f32_e32 v105, v105, v156
	v_mul_f32_e32 v109, v109, v157
	v_mul_f32_e32 v107, v106, v107
	v_mul_f32_e32 v126, v126, v127
	v_mul_f32_e32 v112, v112, v113
	v_mul_f32_e32 v113, v116, v117
	v_mul_f32_e32 v114, v114, v115
	v_mul_f32_e32 v115, v118, v119
	v_mul_f32_e32 v116, v104, v105
	v_mul_f32_e32 v108, v108, v109
	v_cvt_pk_bf16_f32 v104, v126, v112
	v_cvt_pk_bf16_f32 v105, v113, v114
	v_cvt_pk_bf16_f32 v106, v115, v116
	v_cvt_pk_bf16_f32 v107, v108, v107
	flat_store_dwordx4 v[110:111], v[104:107]
	s_nop 0
	s_nop 0
	v_mov_b32_e32 v105, v96
	v_mov_b32_e32 v96, v101
	v_mov_b32_e32 v101, v98
	v_mov_b32_e32 v98, v103
	v_mov_b32_e32 v103, v88
	v_mov_b32_e32 v88, v93
	v_mov_b32_e32 v93, v90
	v_mov_b32_e32 v90, v95
	v_mov_b32_e32 v104, v100
	v_mov_b32_e32 v100, v102
	v_mov_b32_e32 v102, v92
	v_mov_b32_e32 v92, v94
	v_or_b32_e32 v94, 32, v148
	v_mad_i64_i32 v[94:95], s[0:1], v94, s3, v[124:125]
	v_lshl_add_u64 v[94:95], v[94:95], 0, s[26:27]
	v_lshl_add_u64 v[94:95], v[94:95], 0, s[76:77]
	v_lshl_add_u64 v[94:95], v[94:95], 0, v[176:177]
	v_fmamk_f32 v106, v183, 0x3a800000, v224
	v_mul_f32_e32 v107, 0x4b800000, v106
	v_cmp_gt_f32_e32 vcc, s33, v106
	s_nop 1
	v_cndmask_b32_e32 v106, v106, v107, vcc
	v_rsq_f32_e32 v106, v106
	s_nop 0
	v_mul_f32_e32 v107, 0x45800000, v106
	v_cndmask_b32_e32 v106, v106, v107, vcc
	v_pk_fma_f32 v[90:91], v[90:91], v[106:107], v[82:83] op_sel_hi:[1,0,1]
	v_pk_fma_f32 v[104:105], v[104:105], v[106:107], v[120:121] op_sel_hi:[1,0,1]
	v_pk_fma_f32 v[96:97], v[96:97], v[106:107], v[84:85] op_sel_hi:[1,0,1]
	v_pk_fma_f32 v[100:101], v[100:101], v[106:107], v[122:123] op_sel_hi:[1,0,1]
	v_pk_fma_f32 v[98:99], v[98:99], v[106:107], v[86:87] op_sel_hi:[1,0,1]
	v_pk_fma_f32 v[102:103], v[102:103], v[106:107], v[132:133] op_sel_hi:[1,0,1]
	v_pk_fma_f32 v[88:89], v[88:89], v[106:107], v[80:81] op_sel_hi:[1,0,1]
	v_pk_fma_f32 v[92:93], v[92:93], v[106:107], v[134:135] op_sel_hi:[1,0,1]
	v_mul_f32_e32 v113, 0xbfb8aa3b, v91
	v_mul_f32_e32 v106, 0xbfb8aa3b, v105
	v_mul_f32_e32 v107, 0xbfb8aa3b, v97
	v_mul_f32_e32 v108, 0xbfb8aa3b, v101
	v_mul_f32_e32 v109, 0xbfb8aa3b, v99
	v_mul_f32_e32 v110, 0xbfb8aa3b, v103
	v_mul_f32_e32 v111, 0xbfb8aa3b, v89
	v_mul_f32_e32 v112, 0xbfb8aa3b, v93
	v_exp_f32_e32 v113, v113
	v_exp_f32_e32 v106, v106
	v_exp_f32_e32 v107, v107
	v_exp_f32_e32 v108, v108
	v_exp_f32_e32 v109, v109
	v_exp_f32_e32 v110, v110
	v_exp_f32_e32 v111, v111
	v_exp_f32_e32 v112, v112
	v_add_f32_e32 v113, 1.0, v113
	v_add_f32_e32 v106, 1.0, v106
	v_add_f32_e32 v107, 1.0, v107
	v_add_f32_e32 v108, 1.0, v108
	v_add_f32_e32 v109, 1.0, v109
	v_add_f32_e32 v110, 1.0, v110
	v_add_f32_e32 v111, 1.0, v111
	v_add_f32_e32 v112, 1.0, v112
	v_rcp_f32_e32 v113, v113
	v_rcp_f32_e32 v106, v106
	v_rcp_f32_e32 v107, v107
	v_rcp_f32_e32 v108, v108
	v_rcp_f32_e32 v109, v109
	v_rcp_f32_e32 v110, v110
	v_rcp_f32_e32 v111, v111
	v_rcp_f32_e32 v112, v112
	v_mul_f32_e32 v91, v91, v113
	v_mul_f32_e32 v105, v105, v106
	v_mul_f32_e32 v97, v97, v107
	v_mul_f32_e32 v101, v101, v108
	v_mul_f32_e32 v99, v99, v109
	v_mul_f32_e32 v103, v103, v110
	v_mul_f32_e32 v89, v89, v111
	v_mul_f32_e32 v93, v93, v112
	v_mul_f32_e32 v91, v90, v91
	v_mul_f32_e32 v104, v104, v105
	v_mul_f32_e32 v96, v96, v97
	v_mul_f32_e32 v97, v100, v101
	v_mul_f32_e32 v98, v98, v99
	v_mul_f32_e32 v99, v102, v103
	v_mul_f32_e32 v100, v88, v89
	v_mul_f32_e32 v92, v92, v93
	v_cvt_pk_bf16_f32 v88, v104, v96
	v_cvt_pk_bf16_f32 v89, v97, v98
	v_cvt_pk_bf16_f32 v90, v99, v100
	v_cvt_pk_bf16_f32 v91, v92, v91
	flat_store_dwordx4 v[94:95], v[88:91]
	s_nop 0
	s_nop 0
	v_mov_b32_e32 v89, v72
	v_mov_b32_e32 v72, v77
	v_mov_b32_e32 v77, v74
	v_mov_b32_e32 v74, v79
	v_mov_b32_e32 v79, v64
	v_mov_b32_e32 v64, v69
	v_mov_b32_e32 v69, v66
	v_mov_b32_e32 v66, v71
	v_mov_b32_e32 v88, v76
	v_mov_b32_e32 v76, v78
	v_mov_b32_e32 v78, v68
	v_mov_b32_e32 v68, v70
	v_or_b32_e32 v70, 48, v148
	v_mad_i64_i32 v[70:71], s[0:1], v70, s3, v[124:125]
	v_lshl_add_u64 v[70:71], v[70:71], 0, s[26:27]
	v_lshl_add_u64 v[70:71], v[70:71], 0, s[76:77]
	v_lshl_add_u64 v[70:71], v[70:71], 0, v[176:177]
	v_fmamk_f32 v90, v184, 0x3a800000, v224
	v_mul_f32_e32 v91, 0x4b800000, v90
; __device__ __forceinline__ float sigm(float v) { return __builtin_amdgcn_rcpf(1.f + __builtin_amdgcn_exp2f(-1.4426950408889634f * v)); }
; __device__ __forceinline__ unsigned pkbf(float lo, float hi) { return pg8::cvt_pk_bf16(lo, hi); }
;     __device__ __forceinline__ void operator()(const f32x4 (&acc)[2][2][4][2], const Unit& u, int wr, int wc, int fr, int fq) const {
;         const int pn = u.pn, pm = u.pm;
;         const int v = pm >= 64 ? 2 : (pm >> 5);
;         const int cb = pn * 256 + wc * 32 + 8 * fq;
;         f32x4 bv[2][2];
; #pragma unroll
;         for (int bj = 0; bj < 2; ++bj)
; #pragma unroll
;             for (int n = 0; n < 2; ++n) bv[bj][n] = *(const f32x4*)(bias + v * FFI + cb + 128 * bj + 4 * n);
; #pragma unroll
;         for (int ai = 0; ai < 2; ++ai)
; #pragma unroll
;             for (int m = 0; m < 4; ++m) {
;                 const int row = pm * 256 + ai * 128 + wr * 64 + m * 16 + fr;
;                 const float rinv = rsqrtf(rowsq[row] * (1.f / DM) + EPSN);
;                 f32x4 o[2];
; #pragma unroll
;                 for (int n = 0; n < 2; ++n) {
;                     const f32x4 g = acc[ai][0][m][n] * rinv + bv[0][n], up = acc[ai][1][m][n] * rinv + bv[1][n];
; #pragma unroll
;                     for (int j = 0; j < 4; ++j) o[n][j] = g[j] * sigm(g[j]) * up[j];
;                 }
;                 u32x4 w; w.x = pkbf(o[0][0], o[0][1]); w.y = pkbf(o[0][2], o[0][3]); w.z = pkbf(o[1][0], o[1][1]); w.w = pkbf(o[1][2], o[1][3]);
;                 *(u32x4*)(act + (size_t)row * FFH + pn * 128 + wc * 32 + 8 * fq) = w;
;             }
;     }
	v_cmp_gt_f32_e32 vcc, s33, v90
	s_nop 1
	v_cndmask_b32_e32 v90, v90, v91, vcc
	v_rsq_f32_e32 v90, v90
	s_nop 0
	v_mul_f32_e32 v91, 0x45800000, v90
	v_cndmask_b32_e32 v90, v90, v91, vcc
	v_pk_fma_f32 v[66:67], v[66:67], v[90:91], v[82:83] op_sel_hi:[1,0,1]
	v_pk_fma_f32 v[88:89], v[88:89], v[90:91], v[120:121] op_sel_hi:[1,0,1]
	v_pk_fma_f32 v[72:73], v[72:73], v[90:91], v[84:85] op_sel_hi:[1,0,1]
	v_pk_fma_f32 v[76:77], v[76:77], v[90:91], v[122:123] op_sel_hi:[1,0,1]
	v_pk_fma_f32 v[74:75], v[74:75], v[90:91], v[86:87] op_sel_hi:[1,0,1]
	v_pk_fma_f32 v[78:79], v[78:79], v[90:91], v[132:133] op_sel_hi:[1,0,1]
	v_pk_fma_f32 v[64:65], v[64:65], v[90:91], v[80:81] op_sel_hi:[1,0,1]
	v_pk_fma_f32 v[68:69], v[68:69], v[90:91], v[134:135] op_sel_hi:[1,0,1]
	v_mul_f32_e32 v97, 0xbfb8aa3b, v67
	v_mul_f32_e32 v90, 0xbfb8aa3b, v89
	v_mul_f32_e32 v91, 0xbfb8aa3b, v73
	v_mul_f32_e32 v92, 0xbfb8aa3b, v77
	v_mul_f32_e32 v93, 0xbfb8aa3b, v75
	v_mul_f32_e32 v94, 0xbfb8aa3b, v79
	v_mul_f32_e32 v95, 0xbfb8aa3b, v65
	v_mul_f32_e32 v96, 0xbfb8aa3b, v69
	v_exp_f32_e32 v97, v97
	v_exp_f32_e32 v90, v90
	v_exp_f32_e32 v91, v91
	v_exp_f32_e32 v92, v92
	v_exp_f32_e32 v93, v93
	v_exp_f32_e32 v94, v94
	v_exp_f32_e32 v95, v95
	v_exp_f32_e32 v96, v96
	v_add_f32_e32 v97, 1.0, v97
	v_add_f32_e32 v90, 1.0, v90
	v_add_f32_e32 v91, 1.0, v91
	v_add_f32_e32 v92, 1.0, v92
	v_add_f32_e32 v93, 1.0, v93
	v_add_f32_e32 v94, 1.0, v94
	v_add_f32_e32 v95, 1.0, v95
	v_add_f32_e32 v96, 1.0, v96
	v_rcp_f32_e32 v97, v97
	v_rcp_f32_e32 v90, v90
	v_rcp_f32_e32 v91, v91
	v_rcp_f32_e32 v92, v92
	v_rcp_f32_e32 v93, v93
	v_rcp_f32_e32 v94, v94
	v_rcp_f32_e32 v95, v95
	v_rcp_f32_e32 v96, v96
	v_mul_f32_e32 v67, v67, v97
	v_mul_f32_e32 v89, v89, v90
	v_mul_f32_e32 v73, v73, v91
	v_mul_f32_e32 v77, v77, v92
	v_mul_f32_e32 v75, v75, v93
	v_mul_f32_e32 v79, v79, v94
	v_mul_f32_e32 v65, v65, v95
	v_mul_f32_e32 v69, v69, v96
	v_mul_f32_e32 v67, v66, v67
	v_mul_f32_e32 v88, v88, v89
	v_mul_f32_e32 v72, v72, v73
	v_mul_f32_e32 v73, v76, v77
	v_mul_f32_e32 v74, v74, v75
	v_mul_f32_e32 v75, v78, v79
	v_mul_f32_e32 v76, v64, v65
	v_mul_f32_e32 v68, v68, v69
	v_cvt_pk_bf16_f32 v64, v88, v72
	v_cvt_pk_bf16_f32 v65, v73, v74
	v_cvt_pk_bf16_f32 v66, v75, v76
	v_cvt_pk_bf16_f32 v67, v68, v67
	flat_store_dwordx4 v[70:71], v[64:67]
	s_nop 0
	s_nop 0
	v_mov_b32_e32 v65, v56
	v_mov_b32_e32 v56, v61
	v_mov_b32_e32 v61, v58
	v_mov_b32_e32 v58, v63
	v_mov_b32_e32 v63, v48
	v_mov_b32_e32 v48, v53
	v_mov_b32_e32 v53, v50
	v_mov_b32_e32 v50, v55
	v_mov_b32_e32 v64, v60
	v_mov_b32_e32 v60, v62
	v_mov_b32_e32 v62, v52
	v_mov_b32_e32 v52, v54
	v_add_u32_e32 v54, 0x80, v148
	v_mad_i64_i32 v[54:55], s[0:1], v54, s3, v[124:125]
	v_lshl_add_u64 v[54:55], v[54:55], 0, s[26:27]
	v_lshl_add_u64 v[54:55], v[54:55], 0, s[76:77]
	v_lshl_add_u64 v[54:55], v[54:55], 0, v[176:177]
	v_fmamk_f32 v66, v185, 0x3a800000, v224
	v_mul_f32_e32 v67, 0x4b800000, v66
	v_cmp_gt_f32_e32 vcc, s33, v66
	s_nop 1
	v_cndmask_b32_e32 v66, v66, v67, vcc
	v_rsq_f32_e32 v66, v66
	s_nop 0
	v_mul_f32_e32 v67, 0x45800000, v66
	v_cndmask_b32_e32 v66, v66, v67, vcc
	v_pk_fma_f32 v[50:51], v[50:51], v[66:67], v[82:83] op_sel_hi:[1,0,1]
	v_pk_fma_f32 v[64:65], v[64:65], v[66:67], v[120:121] op_sel_hi:[1,0,1]
	v_pk_fma_f32 v[56:57], v[56:57], v[66:67], v[84:85] op_sel_hi:[1,0,1]
	v_pk_fma_f32 v[60:61], v[60:61], v[66:67], v[122:123] op_sel_hi:[1,0,1]
	v_pk_fma_f32 v[58:59], v[58:59], v[66:67], v[86:87] op_sel_hi:[1,0,1]
	v_pk_fma_f32 v[62:63], v[62:63], v[66:67], v[132:133] op_sel_hi:[1,0,1]
	v_pk_fma_f32 v[48:49], v[48:49], v[66:67], v[80:81] op_sel_hi:[1,0,1]
	v_pk_fma_f32 v[52:53], v[52:53], v[66:67], v[134:135] op_sel_hi:[1,0,1]
	v_mul_f32_e32 v73, 0xbfb8aa3b, v51
	v_mul_f32_e32 v66, 0xbfb8aa3b, v65
	v_mul_f32_e32 v67, 0xbfb8aa3b, v57
	v_mul_f32_e32 v68, 0xbfb8aa3b, v61
	v_mul_f32_e32 v69, 0xbfb8aa3b, v59
	v_mul_f32_e32 v70, 0xbfb8aa3b, v63
	v_mul_f32_e32 v71, 0xbfb8aa3b, v49
	v_mul_f32_e32 v72, 0xbfb8aa3b, v53
	v_exp_f32_e32 v73, v73
	v_exp_f32_e32 v66, v66
	v_exp_f32_e32 v67, v67
	v_exp_f32_e32 v68, v68
	v_exp_f32_e32 v69, v69
	v_exp_f32_e32 v70, v70
	v_exp_f32_e32 v71, v71
	v_exp_f32_e32 v72, v72
	v_add_f32_e32 v73, 1.0, v73
	v_add_f32_e32 v66, 1.0, v66
	v_add_f32_e32 v67, 1.0, v67
	v_add_f32_e32 v68, 1.0, v68
	v_add_f32_e32 v69, 1.0, v69
	v_add_f32_e32 v70, 1.0, v70
	v_add_f32_e32 v71, 1.0, v71
	v_add_f32_e32 v72, 1.0, v72
	v_rcp_f32_e32 v73, v73
	v_rcp_f32_e32 v66, v66
	v_rcp_f32_e32 v67, v67
	v_rcp_f32_e32 v68, v68
	v_rcp_f32_e32 v69, v69
	v_rcp_f32_e32 v70, v70
	v_rcp_f32_e32 v71, v71
	v_rcp_f32_e32 v72, v72
	v_mul_f32_e32 v51, v51, v73
	v_mul_f32_e32 v65, v65, v66
	v_mul_f32_e32 v57, v57, v67
	v_mul_f32_e32 v61, v61, v68
	v_mul_f32_e32 v59, v59, v69
	v_mul_f32_e32 v63, v63, v70
	v_mul_f32_e32 v49, v49, v71
	v_mul_f32_e32 v53, v53, v72
	v_mul_f32_e32 v51, v50, v51
	v_mul_f32_e32 v64, v64, v65
	v_mul_f32_e32 v56, v56, v57
	v_mul_f32_e32 v57, v60, v61
	v_mul_f32_e32 v58, v58, v59
	v_mul_f32_e32 v59, v62, v63
	v_mul_f32_e32 v60, v48, v49
	v_mul_f32_e32 v52, v52, v53
	v_cvt_pk_bf16_f32 v48, v64, v56
	v_cvt_pk_bf16_f32 v49, v57, v58
	v_cvt_pk_bf16_f32 v50, v59, v60
	v_cvt_pk_bf16_f32 v51, v52, v51
	flat_store_dwordx4 v[54:55], v[48:51]
	s_nop 0
	s_nop 0
	v_mov_b32_e32 v49, v40
	v_mov_b32_e32 v40, v45
	v_mov_b32_e32 v45, v42
	v_mov_b32_e32 v42, v47
	v_mov_b32_e32 v47, v32
	v_mov_b32_e32 v32, v37
	v_mov_b32_e32 v37, v34
	v_mov_b32_e32 v34, v39
	v_mov_b32_e32 v48, v44
	v_mov_b32_e32 v44, v46
	v_mov_b32_e32 v46, v36
	v_mov_b32_e32 v36, v38
	v_add_u32_e32 v38, 0x90, v148
	v_mad_i64_i32 v[38:39], s[0:1], v38, s3, v[124:125]
	v_lshl_add_u64 v[38:39], v[38:39], 0, s[26:27]
; __device__ __forceinline__ float sigm(float v) { return __builtin_amdgcn_rcpf(1.f + __builtin_amdgcn_exp2f(-1.4426950408889634f * v)); }
; __device__ __forceinline__ unsigned pkbf(float lo, float hi) { return pg8::cvt_pk_bf16(lo, hi); }
;     __device__ __forceinline__ void operator()(const f32x4 (&acc)[2][2][4][2], const Unit& u, int wr, int wc, int fr, int fq) const {
;         const int pn = u.pn, pm = u.pm;
;         const int v = pm >= 64 ? 2 : (pm >> 5);
;         const int cb = pn * 256 + wc * 32 + 8 * fq;
;         f32x4 bv[2][2];
; #pragma unroll
;         for (int bj = 0; bj < 2; ++bj)
; #pragma unroll
;             for (int n = 0; n < 2; ++n) bv[bj][n] = *(const f32x4*)(bias + v * FFI + cb + 128 * bj + 4 * n);
; #pragma unroll
;         for (int ai = 0; ai < 2; ++ai)
; #pragma unroll
;             for (int m = 0; m < 4; ++m) {
;                 const int row = pm * 256 + ai * 128 + wr * 64 + m * 16 + fr;
;                 const float rinv = rsqrtf(rowsq[row] * (1.f / DM) + EPSN);
;                 f32x4 o[2];
; #pragma unroll
;                 for (int n = 0; n < 2; ++n) {
;                     const f32x4 g = acc[ai][0][m][n] * rinv + bv[0][n], up = acc[ai][1][m][n] * rinv + bv[1][n];
; #pragma unroll
;                     for (int j = 0; j < 4; ++j) o[n][j] = g[j] * sigm(g[j]) * up[j];
;                 }
;                 u32x4 w; w.x = pkbf(o[0][0], o[0][1]); w.y = pkbf(o[0][2], o[0][3]); w.z = pkbf(o[1][0], o[1][1]); w.w = pkbf(o[1][2], o[1][3]);
;                 *(u32x4*)(act + (size_t)row * FFH + pn * 128 + wc * 32 + 8 * fq) = w;
;             }
;     }
	v_lshl_add_u64 v[38:39], v[38:39], 0, s[76:77]
	v_lshl_add_u64 v[38:39], v[38:39], 0, v[176:177]
	v_fmamk_f32 v50, v186, 0x3a800000, v224
	v_mul_f32_e32 v51, 0x4b800000, v50
	v_cmp_gt_f32_e32 vcc, s33, v50
	s_nop 1
	v_cndmask_b32_e32 v50, v50, v51, vcc
	v_rsq_f32_e32 v50, v50
	s_nop 0
	v_mul_f32_e32 v51, 0x45800000, v50
	v_cndmask_b32_e32 v50, v50, v51, vcc
	v_pk_fma_f32 v[34:35], v[34:35], v[50:51], v[82:83] op_sel_hi:[1,0,1]
	v_pk_fma_f32 v[48:49], v[48:49], v[50:51], v[120:121] op_sel_hi:[1,0,1]
	v_pk_fma_f32 v[40:41], v[40:41], v[50:51], v[84:85] op_sel_hi:[1,0,1]
	v_pk_fma_f32 v[44:45], v[44:45], v[50:51], v[122:123] op_sel_hi:[1,0,1]
	v_pk_fma_f32 v[42:43], v[42:43], v[50:51], v[86:87] op_sel_hi:[1,0,1]
	v_pk_fma_f32 v[46:47], v[46:47], v[50:51], v[132:133] op_sel_hi:[1,0,1]
	v_pk_fma_f32 v[32:33], v[32:33], v[50:51], v[80:81] op_sel_hi:[1,0,1]
	v_pk_fma_f32 v[36:37], v[36:37], v[50:51], v[134:135] op_sel_hi:[1,0,1]
	v_mul_f32_e32 v57, 0xbfb8aa3b, v35
	v_mul_f32_e32 v50, 0xbfb8aa3b, v49
	v_mul_f32_e32 v51, 0xbfb8aa3b, v41
	v_mul_f32_e32 v52, 0xbfb8aa3b, v45
	v_mul_f32_e32 v53, 0xbfb8aa3b, v43
	v_mul_f32_e32 v54, 0xbfb8aa3b, v47
	v_mul_f32_e32 v55, 0xbfb8aa3b, v33
	v_mul_f32_e32 v56, 0xbfb8aa3b, v37
	v_exp_f32_e32 v57, v57
	v_exp_f32_e32 v50, v50
	v_exp_f32_e32 v51, v51
	v_exp_f32_e32 v52, v52
	v_exp_f32_e32 v53, v53
	v_exp_f32_e32 v54, v54
	v_exp_f32_e32 v55, v55
	v_exp_f32_e32 v56, v56
	v_add_f32_e32 v57, 1.0, v57
	v_add_f32_e32 v50, 1.0, v50
	v_add_f32_e32 v51, 1.0, v51
	v_add_f32_e32 v52, 1.0, v52
	v_add_f32_e32 v53, 1.0, v53
	v_add_f32_e32 v54, 1.0, v54
	v_add_f32_e32 v55, 1.0, v55
	v_add_f32_e32 v56, 1.0, v56
	v_rcp_f32_e32 v57, v57
	v_rcp_f32_e32 v50, v50
	v_rcp_f32_e32 v51, v51
	v_rcp_f32_e32 v52, v52
	v_rcp_f32_e32 v53, v53
	v_rcp_f32_e32 v54, v54
	v_rcp_f32_e32 v55, v55
	v_rcp_f32_e32 v56, v56
	v_mul_f32_e32 v35, v35, v57
	v_mul_f32_e32 v49, v49, v50
	v_mul_f32_e32 v41, v41, v51
	v_mul_f32_e32 v45, v45, v52
	v_mul_f32_e32 v43, v43, v53
	v_mul_f32_e32 v47, v47, v54
	v_mul_f32_e32 v33, v33, v55
	v_mul_f32_e32 v37, v37, v56
	v_mul_f32_e32 v35, v34, v35
	v_mul_f32_e32 v48, v48, v49
	v_mul_f32_e32 v40, v40, v41
	v_mul_f32_e32 v41, v44, v45
	v_mul_f32_e32 v42, v42, v43
	v_mul_f32_e32 v43, v46, v47
	v_mul_f32_e32 v44, v32, v33
	v_mul_f32_e32 v36, v36, v37
	v_cvt_pk_bf16_f32 v32, v48, v40
	v_cvt_pk_bf16_f32 v33, v41, v42
	v_cvt_pk_bf16_f32 v34, v43, v44
	v_cvt_pk_bf16_f32 v35, v36, v35
	flat_store_dwordx4 v[38:39], v[32:35]
	s_nop 0
	s_nop 0
	v_mov_b32_e32 v33, v24
	v_mov_b32_e32 v24, v29
	v_mov_b32_e32 v29, v26
	v_mov_b32_e32 v26, v31
	v_mov_b32_e32 v31, v16
	v_mov_b32_e32 v16, v21
	v_mov_b32_e32 v21, v18
	v_mov_b32_e32 v18, v23
	v_mov_b32_e32 v32, v28
	v_mov_b32_e32 v28, v30
	v_mov_b32_e32 v30, v20
	v_mov_b32_e32 v20, v22
	v_add_u32_e32 v22, 0xa0, v148
	v_mad_i64_i32 v[22:23], s[0:1], v22, s3, v[124:125]
	v_lshl_add_u64 v[22:23], v[22:23], 0, s[26:27]
	v_lshl_add_u64 v[22:23], v[22:23], 0, s[76:77]
	v_lshl_add_u64 v[22:23], v[22:23], 0, v[176:177]
	v_fmamk_f32 v34, v187, 0x3a800000, v224
	v_mul_f32_e32 v35, 0x4b800000, v34
	v_cmp_gt_f32_e32 vcc, s33, v34
	s_nop 1
	v_cndmask_b32_e32 v34, v34, v35, vcc
	v_rsq_f32_e32 v34, v34
	s_nop 0
	v_mul_f32_e32 v35, 0x45800000, v34
	v_cndmask_b32_e32 v34, v34, v35, vcc
	v_pk_fma_f32 v[18:19], v[18:19], v[34:35], v[82:83] op_sel_hi:[1,0,1]
	v_pk_fma_f32 v[32:33], v[32:33], v[34:35], v[120:121] op_sel_hi:[1,0,1]
	v_pk_fma_f32 v[24:25], v[24:25], v[34:35], v[84:85] op_sel_hi:[1,0,1]
	v_pk_fma_f32 v[28:29], v[28:29], v[34:35], v[122:123] op_sel_hi:[1,0,1]
	v_pk_fma_f32 v[26:27], v[26:27], v[34:35], v[86:87] op_sel_hi:[1,0,1]
	v_pk_fma_f32 v[30:31], v[30:31], v[34:35], v[132:133] op_sel_hi:[1,0,1]
	v_pk_fma_f32 v[16:17], v[16:17], v[34:35], v[80:81] op_sel_hi:[1,0,1]
	v_pk_fma_f32 v[20:21], v[20:21], v[34:35], v[134:135] op_sel_hi:[1,0,1]
	v_mul_f32_e32 v41, 0xbfb8aa3b, v19
	v_mul_f32_e32 v34, 0xbfb8aa3b, v33
	v_mul_f32_e32 v35, 0xbfb8aa3b, v25
	v_mul_f32_e32 v36, 0xbfb8aa3b, v29
	v_mul_f32_e32 v37, 0xbfb8aa3b, v27
	v_mul_f32_e32 v38, 0xbfb8aa3b, v31
	v_mul_f32_e32 v39, 0xbfb8aa3b, v17
	v_mul_f32_e32 v40, 0xbfb8aa3b, v21
	v_exp_f32_e32 v41, v41
	v_exp_f32_e32 v34, v34
; #define PG8_BAR __builtin_amdgcn_s_barrier()
; __device__ __forceinline__ float sigm(float v) { return __builtin_amdgcn_rcpf(1.f + __builtin_amdgcn_exp2f(-1.4426950408889634f * v)); }
; __device__ __forceinline__ unsigned pkbf(float lo, float hi) { return pg8::cvt_pk_bf16(lo, hi); }
; template <class Epi, class Sched, bool ALIGN_EPI = false, bool SP2 = false>
; __device__ __forceinline__ void gemm_phase(PG8_LAS unsigned char* lds, const Gemm g, const Sched& S, const Epi& E) {
;     ...
;         if constexpr (!Epi::AFTER_DRAIN) { E(acc, cur, wr, wc, fr, fq); S.done(cur); }
;         if (!has_next) break;
; #pragma unroll
;         for (int a = 0; a < 2; ++a)
; #pragma unroll
;             for (int b = 0; b < 2; ++b)
; #pragma unroll
;                 for (int m = 0; m < 4; ++m)
; #pragma unroll
;                     for (int n = 0; n < 2; ++n) acc[a][b][m][n] = (f32x4){0.f, 0.f, 0.f, 0.f};
;         cur = nxt; cA = nA; cB = nB; ++ui;
;         if constexpr (ALIGN_EPI) { if (wr == 1) PG8_BAR; }
;     __device__ __forceinline__ void operator()(const f32x4 (&acc)[2][2][4][2], const Unit& u, int wr, int wc, int fr, int fq) const {
;         const int pn = u.pn, pm = u.pm;
;         const int v = pm >= 64 ? 2 : (pm >> 5);
;         const int cb = pn * 256 + wc * 32 + 8 * fq;
;         f32x4 bv[2][2];
; #pragma unroll
;         for (int bj = 0; bj < 2; ++bj)
; #pragma unroll
;             for (int n = 0; n < 2; ++n) bv[bj][n] = *(const f32x4*)(bias + v * FFI + cb + 128 * bj + 4 * n);
; #pragma unroll
;         for (int ai = 0; ai < 2; ++ai)
; #pragma unroll
;             for (int m = 0; m < 4; ++m) {
;                 const int row = pm * 256 + ai * 128 + wr * 64 + m * 16 + fr;
;                 const float rinv = rsqrtf(rowsq[row] * (1.f / DM) + EPSN);
;                 f32x4 o[2];
; #pragma unroll
;                 for (int n = 0; n < 2; ++n) {
;                     const f32x4 g = acc[ai][0][m][n] * rinv + bv[0][n], up = acc[ai][1][m][n] * rinv + bv[1][n];
; #pragma unroll
;                     for (int j = 0; j < 4; ++j) o[n][j] = g[j] * sigm(g[j]) * up[j];
;                 }
;                 u32x4 w; w.x = pkbf(o[0][0], o[0][1]); w.y = pkbf(o[0][2], o[0][3]); w.z = pkbf(o[1][0], o[1][1]); w.w = pkbf(o[1][2], o[1][3]);
;                 *(u32x4*)(act + (size_t)row * FFH + pn * 128 + wc * 32 + 8 * fq) = w;
;             }
;     }
	v_exp_f32_e32 v35, v35
	v_exp_f32_e32 v36, v36
	v_exp_f32_e32 v37, v37
	v_exp_f32_e32 v38, v38
	v_exp_f32_e32 v39, v39
	v_exp_f32_e32 v40, v40
	v_add_f32_e32 v41, 1.0, v41
	v_add_f32_e32 v34, 1.0, v34
	v_add_f32_e32 v35, 1.0, v35
	v_add_f32_e32 v36, 1.0, v36
	v_add_f32_e32 v37, 1.0, v37
	v_add_f32_e32 v38, 1.0, v38
	v_add_f32_e32 v39, 1.0, v39
	v_add_f32_e32 v40, 1.0, v40
	v_rcp_f32_e32 v41, v41
	v_rcp_f32_e32 v34, v34
	v_rcp_f32_e32 v35, v35
	v_rcp_f32_e32 v36, v36
	v_rcp_f32_e32 v37, v37
	v_rcp_f32_e32 v38, v38
	v_rcp_f32_e32 v39, v39
	v_rcp_f32_e32 v40, v40
	v_mul_f32_e32 v19, v19, v41
	v_mul_f32_e32 v33, v33, v34
	v_mul_f32_e32 v25, v25, v35
	v_mul_f32_e32 v29, v29, v36
	v_mul_f32_e32 v27, v27, v37
	v_mul_f32_e32 v31, v31, v38
	v_mul_f32_e32 v17, v17, v39
	v_mul_f32_e32 v21, v21, v40
	v_mul_f32_e32 v19, v18, v19
	v_mul_f32_e32 v32, v32, v33
	v_mul_f32_e32 v24, v24, v25
	v_mul_f32_e32 v25, v28, v29
	v_mul_f32_e32 v26, v26, v27
	v_mul_f32_e32 v27, v30, v31
	v_mul_f32_e32 v28, v16, v17
	v_mul_f32_e32 v20, v20, v21
	v_cvt_pk_bf16_f32 v16, v32, v24
	v_cvt_pk_bf16_f32 v17, v25, v26
	v_cvt_pk_bf16_f32 v18, v27, v28
	v_cvt_pk_bf16_f32 v19, v20, v19
	flat_store_dwordx4 v[22:23], v[16:19]
	s_nop 0
	s_andn2_b64 vcc, exec, s[4:5]
	v_mov_b32_e32 v16, v12
	v_mov_b32_e32 v12, v14
	v_mov_b32_e32 v14, v4
	v_mov_b32_e32 v4, v6
	v_add_u32_e32 v6, 0xb0, v148
	v_mov_b32_e32 v17, v8
	v_mov_b32_e32 v8, v13
	v_mov_b32_e32 v13, v10
	v_mov_b32_e32 v10, v15
	v_mov_b32_e32 v15, v0
	v_mov_b32_e32 v0, v5
	v_mov_b32_e32 v5, v2
	v_mov_b32_e32 v2, v7
	v_mad_i64_i32 v[6:7], s[0:1], v6, s3, v[124:125]
	v_lshl_add_u64 v[6:7], v[6:7], 0, s[26:27]
	v_lshl_add_u64 v[6:7], v[6:7], 0, s[76:77]
	v_lshl_add_u64 v[6:7], v[6:7], 0, v[176:177]
	v_fmamk_f32 v18, v188, 0x3a800000, v224
	v_mul_f32_e32 v19, 0x4b800000, v18
	v_cmp_gt_f32_e64 s[0:1], s33, v18
	s_nop 1
	v_cndmask_b32_e64 v18, v18, v19, s[0:1]
	v_rsq_f32_e32 v18, v18
	s_nop 0
	v_mul_f32_e32 v19, 0x45800000, v18
	v_cndmask_b32_e64 v18, v18, v19, s[0:1]
	v_pk_fma_f32 v[2:3], v[2:3], v[18:19], v[82:83] op_sel_hi:[1,0,1]
	v_pk_fma_f32 v[16:17], v[16:17], v[18:19], v[120:121] op_sel_hi:[1,0,1]
	v_pk_fma_f32 v[8:9], v[8:9], v[18:19], v[84:85] op_sel_hi:[1,0,1]
	v_pk_fma_f32 v[12:13], v[12:13], v[18:19], v[122:123] op_sel_hi:[1,0,1]
	v_pk_fma_f32 v[10:11], v[10:11], v[18:19], v[86:87] op_sel_hi:[1,0,1]
	v_pk_fma_f32 v[14:15], v[14:15], v[18:19], v[132:133] op_sel_hi:[1,0,1]
	v_pk_fma_f32 v[0:1], v[0:1], v[18:19], v[80:81] op_sel_hi:[1,0,1]
	v_pk_fma_f32 v[4:5], v[4:5], v[18:19], v[134:135] op_sel_hi:[1,0,1]
	v_mul_f32_e32 v25, 0xbfb8aa3b, v3
	v_mul_f32_e32 v18, 0xbfb8aa3b, v17
	v_mul_f32_e32 v19, 0xbfb8aa3b, v9
	v_mul_f32_e32 v20, 0xbfb8aa3b, v13
	v_mul_f32_e32 v21, 0xbfb8aa3b, v11
	v_mul_f32_e32 v22, 0xbfb8aa3b, v15
	v_mul_f32_e32 v23, 0xbfb8aa3b, v1
	v_mul_f32_e32 v24, 0xbfb8aa3b, v5
	v_exp_f32_e32 v25, v25
	v_exp_f32_e32 v18, v18
	v_exp_f32_e32 v19, v19
	v_exp_f32_e32 v20, v20
	v_exp_f32_e32 v21, v21
	v_exp_f32_e32 v22, v22
	v_exp_f32_e32 v23, v23
	v_exp_f32_e32 v24, v24
	v_add_f32_e32 v25, 1.0, v25
	v_add_f32_e32 v18, 1.0, v18
	v_add_f32_e32 v19, 1.0, v19
	v_add_f32_e32 v20, 1.0, v20
	v_add_f32_e32 v21, 1.0, v21
	v_add_f32_e32 v22, 1.0, v22
	v_add_f32_e32 v23, 1.0, v23
	v_add_f32_e32 v24, 1.0, v24
	v_rcp_f32_e32 v25, v25
	v_rcp_f32_e32 v18, v18
	v_rcp_f32_e32 v19, v19
	v_rcp_f32_e32 v20, v20
	v_rcp_f32_e32 v21, v21
	v_rcp_f32_e32 v22, v22
	v_rcp_f32_e32 v23, v23
	v_rcp_f32_e32 v24, v24
	v_mul_f32_e32 v3, v3, v25
	v_mul_f32_e32 v17, v17, v18
	v_mul_f32_e32 v9, v9, v19
	v_mul_f32_e32 v13, v13, v20
	v_mul_f32_e32 v11, v11, v21
	v_mul_f32_e32 v15, v15, v22
	v_mul_f32_e32 v1, v1, v23
	v_mul_f32_e32 v5, v5, v24
	v_mul_f32_e32 v3, v2, v3
	s_mov_b64 s[0:1], -1
	v_mul_f32_e32 v16, v16, v17
	v_mul_f32_e32 v8, v8, v9
	v_mul_f32_e32 v9, v12, v13
	v_mul_f32_e32 v10, v10, v11
	v_mul_f32_e32 v11, v14, v15
	v_mul_f32_e32 v12, v0, v1
	v_mul_f32_e32 v4, v4, v5
	v_cvt_pk_bf16_f32 v0, v16, v8
	v_cvt_pk_bf16_f32 v1, v9, v10
	v_cvt_pk_bf16_f32 v2, v11, v12
	v_cvt_pk_bf16_f32 v3, v4, v3
	flat_store_dwordx4 v[6:7], v[0:3]
	s_cbranch_vccnz .LBB0_1081
	s_andn2_b64 vcc, exec, s[8:9]
	s_cbranch_vccnz .LBB0_1080
	s_barrier
	s_branch .LBB0_1080
